# code placement: PEER u-part gather code shifted by 4 bytes, rest of PEER unchanged
# speedup vs baseline: 1.0110x; 1.0110x over previous
.LBB0_731:
	v_add_u32_e32 v223, s61, v223
	v_cmp_lt_i32_e32 vcc, s101, v223
	s_or_b64 s[34:35], vcc, s[34:35]
	s_andn2_b64 exec, exec, s[34:35]
	s_cbranch_execz .LBB0_802
	s_nop 0
.LBB0_732:
	s_mov_b64 s[36:37], s[16:17]
	v_mov_b32_e32 v17, v214
	v_lshl_add_u32 v12, v223, 9, s62
	v_add_u32_e32 v180, s63, v223
	v_ashrrev_i32_e32 v181, 31, v180
	v_lshl_add_u32 v0, v17, 2, v12
	ds_read2st64_b32 v[150:151], v0 offset0:160 offset1:161
	v_lshlrev_b64 v[0:1], 12, v[180:181]
	v_lshl_add_u64 v[0:1], s[36:37], 0, v[0:1]
	s_mov_b64 s[10:11], 0x1b74b200
	v_lshl_add_u64 v[178:179], v[0:1], 0, s[10:11]
	v_lshlrev_b32_e32 v0, 5, v17
	v_ashrrev_i32_e32 v1, 31, v0
	v_lshl_add_u64 v[0:1], v[0:1], 1, v[178:179]
	global_load_dwordx4 v[2:5], v[0:1], off offset:48
	global_load_dwordx4 v[6:9], v[0:1], off offset:32
	global_load_dwordx4 v[18:21], v[0:1], off offset:16
	global_load_dwordx4 v[22:25], v[0:1], off
	v_mov_b32_e32 v0, v16
	v_lshl_add_u32 v10, v17, 4, v216
	v_and_b32_e32 v158, 15, v17
	s_add_u32 s10, s36, s20
	s_addc_u32 s11, s37, s21
	s_add_u32 s12, s10, 0x9a04000
	s_addc_u32 s13, s11, 0
	v_and_b32_e32 v152, -16, v17
	v_ashrrev_i32_e32 v153, 31, v152
	v_lshlrev_b32_e32 v224, 3, v17
	v_and_b32_e32 v154, 3, v17
	s_mov_b64 s[0:1], 0xda04000
	s_waitcnt vmcnt(3)
	v_lshlrev_b32_e32 v53, 16, v2
	v_and_b32_e32 v55, 0xffff0000, v2
	v_lshlrev_b32_e32 v57, 16, v3
	s_waitcnt vmcnt(0)
	v_lshlrev_b32_e32 v1, 16, v22
	v_and_b32_e32 v13, 0xffff0000, v22
	v_mul_f32_e32 v11, 0x3e800000, v1
	v_mul_f32_e32 v14, 0x3e800000, v13
	v_lshlrev_b32_e32 v15, 16, v23
	v_and_b32_e32 v23, 0xffff0000, v23
	v_mul_f32_e32 v22, 0x3e800000, v15
	v_mul_f32_e32 v26, 0x3e800000, v23
	v_lshlrev_b32_e32 v27, 16, v24
	v_and_b32_e32 v24, 0xffff0000, v24
	v_cvt_scalef32_pk_fp4_f32 v0, v11, v14, 1.0
	v_mul_f32_e32 v28, 0x3e800000, v27
	v_mul_f32_e32 v29, 0x3e800000, v24
	v_lshlrev_b32_e32 v30, 16, v25
	v_and_b32_e32 v25, 0xffff0000, v25
	v_cvt_scalef32_pk_fp4_f32 v0, v22, v26, 1.0 op_sel:[0,0,1,0]
	v_mul_f32_e32 v31, 0x3e800000, v30
	v_mul_f32_e32 v32, 0x3e800000, v25
	v_cvt_scalef32_pk_fp4_f32 v0, v28, v29, 1.0 op_sel:[0,0,0,1]
	v_lshlrev_b32_e32 v11, 16, v18
	v_cvt_scalef32_pk_fp4_f32 v0, v31, v32, 1.0 op_sel:[0,0,1,1]
	v_and_b32_e32 v18, 0xffff0000, v18
	v_and_b32_e32 v59, 0xffff0000, v3
	v_cvt_scalef32_pk_f32_fp4 v[2:3], v0, 1.0
	v_mul_f32_e32 v14, 0x3e800000, v11
	v_mul_f32_e32 v22, 0x3e800000, v18
	v_lshlrev_b32_e32 v26, 16, v19
	v_and_b32_e32 v19, 0xffff0000, v19
	v_fma_f32 v69, v1, s87, -v2
	v_mov_b32_e32 v1, v16
	v_mul_f32_e32 v28, 0x3e800000, v26
	v_mul_f32_e32 v29, 0x3e800000, v19
	v_lshlrev_b32_e32 v31, 16, v20
	v_and_b32_e32 v20, 0xffff0000, v20
	v_cvt_scalef32_pk_fp4_f32 v1, v14, v22, 1.0
	v_mul_f32_e32 v32, 0x3e800000, v31
	v_mul_f32_e32 v33, 0x3e800000, v20
	v_lshlrev_b32_e32 v34, 16, v21
	v_and_b32_e32 v21, 0xffff0000, v21
	v_cvt_scalef32_pk_fp4_f32 v1, v28, v29, 1.0 op_sel:[0,0,1,0]
	v_mul_f32_e32 v35, 0x3e800000, v34
	v_mul_f32_e32 v36, 0x3e800000, v21
	v_cvt_scalef32_pk_fp4_f32 v1, v32, v33, 1.0 op_sel:[0,0,0,1]
	v_lshlrev_b32_e32 v37, 16, v6
	v_cvt_scalef32_pk_fp4_f32 v1, v35, v36, 1.0 op_sel:[0,0,1,1]
	v_and_b32_e32 v39, 0xffff0000, v6
	v_fma_f32 v13, v13, s87, -v3
	v_cvt_scalef32_pk_f32_fp4 v[2:3], v1, 1.0
	v_mul_f32_e32 v38, 0x3e800000, v37
	v_mul_f32_e32 v40, 0x3e800000, v39
	v_lshlrev_b32_e32 v41, 16, v7
	v_and_b32_e32 v43, 0xffff0000, v7
	v_mul_f32_e32 v54, 0x3e800000, v53
	v_mul_f32_e32 v56, 0x3e800000, v55
	v_fma_f32 v11, v11, s87, -v2
	v_fma_f32 v18, v18, s87, -v3
	v_mov_b32_e32 v2, v16
	v_mov_b32_e32 v3, v16
	v_mul_f32_e32 v42, 0x3e800000, v41
	v_mul_f32_e32 v44, 0x3e800000, v43
	v_lshlrev_b32_e32 v45, 16, v8
	v_and_b32_e32 v47, 0xffff0000, v8
	v_mul_f32_e32 v58, 0x3e800000, v57
	v_mul_f32_e32 v60, 0x3e800000, v59
	v_lshlrev_b32_e32 v61, 16, v4
	v_and_b32_e32 v63, 0xffff0000, v4
	v_cvt_scalef32_pk_fp4_f32 v2, v38, v40, 1.0
	v_cvt_scalef32_pk_fp4_f32 v3, v54, v56, 1.0
	v_mul_f32_e32 v46, 0x3e800000, v45
	v_mul_f32_e32 v48, 0x3e800000, v47
	v_lshlrev_b32_e32 v49, 16, v9
	v_and_b32_e32 v51, 0xffff0000, v9
	v_mul_f32_e32 v62, 0x3e800000, v61
	v_mul_f32_e32 v64, 0x3e800000, v63
	v_lshlrev_b32_e32 v65, 16, v5
	v_and_b32_e32 v67, 0xffff0000, v5
	v_cvt_scalef32_pk_fp4_f32 v2, v42, v44, 1.0 op_sel:[0,0,1,0]
	v_cvt_scalef32_pk_fp4_f32 v3, v58, v60, 1.0 op_sel:[0,0,1,0]
	v_mul_f32_e32 v50, 0x3e800000, v49
	v_mul_f32_e32 v52, 0x3e800000, v51
	v_mul_f32_e32 v66, 0x3e800000, v65
	v_mul_f32_e32 v68, 0x3e800000, v67
	v_cvt_scalef32_pk_fp4_f32 v2, v46, v48, 1.0 op_sel:[0,0,0,1]
	v_cvt_scalef32_pk_fp4_f32 v3, v62, v64, 1.0 op_sel:[0,0,0,1]
	v_cvt_scalef32_pk_f32_fp4 v[4:5], v0, 1.0 op_sel:[1,0,0]
	v_cvt_scalef32_pk_fp4_f32 v2, v50, v52, 1.0 op_sel:[0,0,1,1]
	v_cvt_scalef32_pk_fp4_f32 v3, v66, v68, 1.0 op_sel:[0,0,1,1]
	v_cvt_scalef32_pk_f32_fp4 v[6:7], v0, 1.0 op_sel:[0,1,0]
	v_cvt_scalef32_pk_f32_fp4 v[8:9], v0, 1.0 op_sel:[1,1,0]
	v_mul_f32_e32 v70, 4.0, v69
	v_mul_f32_e32 v71, 4.0, v13
	v_fma_f32 v72, v15, s87, -v4
	v_fma_f32 v23, v23, s87, -v5
	v_cvt_scalef32_pk_f32_fp4 v[4:5], v1, 1.0 op_sel:[1,0,0]
	ds_write_b128 v10, v[0:3]
	v_mov_b32_e32 v0, v16
	v_mul_f32_e32 v73, 4.0, v72
	v_mul_f32_e32 v74, 4.0, v23
	v_fma_f32 v27, v27, s87, -v6
	v_fma_f32 v24, v24, s87, -v7
	v_fma_f32 v30, v30, s87, -v8
	v_fma_f32 v25, v25, s87, -v9
	v_cvt_scalef32_pk_f32_fp4 v[6:7], v1, 1.0 op_sel:[0,1,0]
	v_cvt_scalef32_pk_f32_fp4 v[8:9], v1, 1.0 op_sel:[1,1,0]
	v_mul_f32_e32 v22, 4.0, v11
	v_mul_f32_e32 v28, 4.0, v18
	v_fma_f32 v26, v26, s87, -v4
	v_fma_f32 v19, v19, s87, -v5
	v_cvt_scalef32_pk_fp4_f32 v0, v70, v71, 1.0
	v_mov_b32_e32 v1, v16
	v_mul_f32_e32 v75, 4.0, v27
	v_mul_f32_e32 v76, 4.0, v24
	v_mul_f32_e32 v29, 4.0, v26
	v_mul_f32_e32 v32, 4.0, v19
	v_fma_f32 v31, v31, s87, -v6
	v_fma_f32 v20, v20, s87, -v7
	v_cvt_scalef32_pk_fp4_f32 v0, v73, v74, 1.0 op_sel:[0,0,1,0]
	v_cvt_scalef32_pk_fp4_f32 v1, v22, v28, 1.0
	v_mul_f32_e32 v77, 4.0, v30
	v_mul_f32_e32 v78, 4.0, v25
	v_mul_f32_e32 v33, 4.0, v31
	v_mul_f32_e32 v35, 4.0, v20
	v_fma_f32 v34, v34, s87, -v8
	v_fma_f32 v21, v21, s87, -v9
	v_cvt_scalef32_pk_fp4_f32 v0, v75, v76, 1.0 op_sel:[0,0,0,1]
	v_cvt_scalef32_pk_fp4_f32 v1, v29, v32, 1.0 op_sel:[0,0,1,0]
	v_mul_f32_e32 v36, 4.0, v34
	v_mul_f32_e32 v79, 4.0, v21
	v_cvt_scalef32_pk_f32_fp4 v[4:5], v2, 1.0
	v_cvt_scalef32_pk_f32_fp4 v[6:7], v2, 1.0 op_sel:[1,0,0]
	v_cvt_scalef32_pk_f32_fp4 v[8:9], v2, 1.0 op_sel:[0,1,0]
	v_cvt_scalef32_pk_f32_fp4 v[14:15], v2, 1.0 op_sel:[1,1,0]
	v_cvt_scalef32_pk_fp4_f32 v0, v77, v78, 1.0 op_sel:[0,0,1,1]
	v_cvt_scalef32_pk_fp4_f32 v1, v33, v35, 1.0 op_sel:[0,0,0,1]
	v_fma_f32 v37, v37, s87, -v4
	v_fma_f32 v39, v39, s87, -v5
	v_fma_f32 v41, v41, s87, -v6
	v_fma_f32 v43, v43, s87, -v7
	v_fma_f32 v45, v45, s87, -v8
	v_fma_f32 v47, v47, s87, -v9
	v_fma_f32 v49, v49, s87, -v14
	v_fma_f32 v51, v51, s87, -v15
	v_cvt_scalef32_pk_f32_fp4 v[4:5], v3, 1.0
	v_cvt_scalef32_pk_f32_fp4 v[6:7], v3, 1.0 op_sel:[1,0,0]
	v_cvt_scalef32_pk_f32_fp4 v[8:9], v3, 1.0 op_sel:[0,1,0]
	v_cvt_scalef32_pk_f32_fp4 v[14:15], v3, 1.0 op_sel:[1,1,0]
	v_cvt_scalef32_pk_f32_fp4 v[2:3], v0, 1.0
	v_cvt_scalef32_pk_fp4_f32 v1, v36, v79, 1.0 op_sel:[0,0,1,1]
	v_fma_f32 v53, v53, s87, -v4
	v_fma_f32 v55, v55, s87, -v5
	v_fma_f32 v69, v69, 4.0, -v2
	v_fma_f32 v13, v13, 4.0, -v3
	v_cvt_scalef32_pk_f32_fp4 v[2:3], v1, 1.0
	v_mul_f32_e32 v38, 4.0, v37
	v_mul_f32_e32 v40, 4.0, v39
	v_mul_f32_e32 v54, 4.0, v53
	v_mul_f32_e32 v56, 4.0, v55
	v_fma_f32 v57, v57, s87, -v6
	v_fma_f32 v59, v59, s87, -v7
	v_fma_f32 v11, v11, 4.0, -v2
	v_fma_f32 v18, v18, 4.0, -v3
	v_mov_b32_e32 v2, v16
	v_mov_b32_e32 v3, v16
	v_mul_f32_e32 v42, 4.0, v41
	v_mul_f32_e32 v44, 4.0, v43
	v_mul_f32_e32 v58, 4.0, v57
	v_mul_f32_e32 v60, 4.0, v59
	v_fma_f32 v61, v61, s87, -v8
	v_fma_f32 v63, v63, s87, -v9
	v_cvt_scalef32_pk_fp4_f32 v2, v38, v40, 1.0
	v_cvt_scalef32_pk_fp4_f32 v3, v54, v56, 1.0
	v_mul_f32_e32 v46, 4.0, v45
	v_mul_f32_e32 v48, 4.0, v47
	v_mul_f32_e32 v62, 4.0, v61
	v_mul_f32_e32 v64, 4.0, v63
	v_fma_f32 v65, v65, s87, -v14
	v_fma_f32 v67, v67, s87, -v15
	v_cvt_scalef32_pk_fp4_f32 v2, v42, v44, 1.0 op_sel:[0,0,1,0]
	v_cvt_scalef32_pk_fp4_f32 v3, v58, v60, 1.0 op_sel:[0,0,1,0]
	v_mul_f32_e32 v50, 4.0, v49
	v_mul_f32_e32 v52, 4.0, v51
	v_mul_f32_e32 v66, 4.0, v65
	v_mul_f32_e32 v68, 4.0, v67
	v_cvt_scalef32_pk_fp4_f32 v2, v46, v48, 1.0 op_sel:[0,0,0,1]
	v_cvt_scalef32_pk_fp4_f32 v3, v62, v64, 1.0 op_sel:[0,0,0,1]
	v_cvt_scalef32_pk_f32_fp4 v[4:5], v0, 1.0 op_sel:[1,0,0]
	v_cvt_scalef32_pk_fp4_f32 v2, v50, v52, 1.0 op_sel:[0,0,1,1]
	v_cvt_scalef32_pk_fp4_f32 v3, v66, v68, 1.0 op_sel:[0,0,1,1]
	v_cvt_scalef32_pk_f32_fp4 v[6:7], v0, 1.0 op_sel:[0,1,0]
	v_cvt_scalef32_pk_f32_fp4 v[8:9], v0, 1.0 op_sel:[1,1,0]
	v_mul_f32_e32 v70, 4.0, v69
	v_mul_f32_e32 v71, 4.0, v13
	v_fma_f32 v72, v72, 4.0, -v4
	v_fma_f32 v23, v23, 4.0, -v5
	ds_write_b128 v10, v[0:3] offset:1024
	v_mov_b32_e32 v0, v16
	v_mul_f32_e32 v73, 4.0, v72
	v_mul_f32_e32 v74, 4.0, v23
	v_fma_f32 v27, v27, 4.0, -v6
	v_fma_f32 v24, v24, 4.0, -v7
	v_cvt_scalef32_pk_fp4_f32 v0, v70, v71, 1.0
	v_mul_f32_e32 v75, 4.0, v27
	v_mul_f32_e32 v76, 4.0, v24
	v_fma_f32 v30, v30, 4.0, -v8
	v_fma_f32 v25, v25, 4.0, -v9
	v_cvt_scalef32_pk_fp4_f32 v0, v73, v74, 1.0 op_sel:[0,0,1,0]
	v_mul_f32_e32 v77, 4.0, v30
	v_mul_f32_e32 v78, 4.0, v25
	v_cvt_scalef32_pk_f32_fp4 v[4:5], v1, 1.0 op_sel:[1,0,0]
	v_cvt_scalef32_pk_f32_fp4 v[6:7], v1, 1.0 op_sel:[0,1,0]
	v_cvt_scalef32_pk_f32_fp4 v[8:9], v1, 1.0 op_sel:[1,1,0]
	v_cvt_scalef32_pk_fp4_f32 v0, v75, v76, 1.0 op_sel:[0,0,0,1]
	v_fma_f32 v26, v26, 4.0, -v4
	v_fma_f32 v19, v19, 4.0, -v5
	v_fma_f32 v31, v31, 4.0, -v6
	v_fma_f32 v20, v20, 4.0, -v7
	v_fma_f32 v34, v34, 4.0, -v8
	v_fma_f32 v21, v21, 4.0, -v9
	v_cvt_scalef32_pk_f32_fp4 v[4:5], v2, 1.0
	v_cvt_scalef32_pk_f32_fp4 v[6:7], v2, 1.0 op_sel:[1,0,0]
	v_cvt_scalef32_pk_f32_fp4 v[8:9], v2, 1.0 op_sel:[0,1,0]
	v_cvt_scalef32_pk_f32_fp4 v[14:15], v2, 1.0 op_sel:[1,1,0]
	v_cvt_scalef32_pk_fp4_f32 v0, v77, v78, 1.0 op_sel:[0,0,1,1]
	v_fma_f32 v37, v37, 4.0, -v4
	v_fma_f32 v39, v39, 4.0, -v5
	v_fma_f32 v41, v41, 4.0, -v6
	v_fma_f32 v43, v43, 4.0, -v7
	v_fma_f32 v45, v45, 4.0, -v8
	v_fma_f32 v47, v47, 4.0, -v9
	v_fma_f32 v49, v49, 4.0, -v14
	v_fma_f32 v51, v51, 4.0, -v15
	v_cvt_scalef32_pk_f32_fp4 v[4:5], v3, 1.0
	v_cvt_scalef32_pk_f32_fp4 v[6:7], v3, 1.0 op_sel:[1,0,0]
	v_cvt_scalef32_pk_f32_fp4 v[8:9], v3, 1.0 op_sel:[0,1,0]
	v_cvt_scalef32_pk_f32_fp4 v[14:15], v3, 1.0 op_sel:[1,1,0]
	v_cvt_scalef32_pk_f32_fp4 v[2:3], v0, 1.0
	v_fma_f32 v1, v69, 4.0, -v2
	v_fma_f32 v53, v53, 4.0, -v4
	v_fma_f32 v55, v55, 4.0, -v5
	v_cvt_scalef32_pk_f32_fp4 v[4:5], v0, 1.0 op_sel:[1,0,0]
	v_mul_f32_e32 v69, 4.0, v1
	v_fma_f32 v1, v13, 4.0, -v3
	v_mul_f32_e32 v13, 4.0, v1
	v_fma_f32 v1, v72, 4.0, -v4
	v_fma_f32 v57, v57, 4.0, -v6
	v_fma_f32 v59, v59, 4.0, -v7
	v_cvt_scalef32_pk_f32_fp4 v[6:7], v0, 1.0 op_sel:[0,1,0]
	v_mul_f32_e32 v70, 4.0, v1
	v_fma_f32 v1, v23, 4.0, -v5
	v_mul_f32_e32 v23, 4.0, v1
	v_fma_f32 v1, v27, 4.0, -v6
	v_fma_f32 v61, v61, 4.0, -v8
	v_fma_f32 v63, v63, 4.0, -v9
	v_cvt_scalef32_pk_f32_fp4 v[8:9], v0, 1.0 op_sel:[1,1,0]
	v_mul_f32_e32 v27, 4.0, v1
	v_fma_f32 v1, v24, 4.0, -v7
	v_mul_f32_e32 v24, 4.0, v1
	v_fma_f32 v1, v30, 4.0, -v8
	v_mul_f32_e32 v30, 4.0, v1
	v_fma_f32 v1, v25, 4.0, -v9
	v_mul_f32_e32 v22, 4.0, v11
	v_mul_f32_e32 v28, 4.0, v18
	v_mul_f32_e32 v25, 4.0, v1
	v_mov_b32_e32 v1, v16
	v_mul_f32_e32 v29, 4.0, v26
	v_mul_f32_e32 v32, 4.0, v19
	v_cvt_scalef32_pk_fp4_f32 v1, v22, v28, 1.0
	v_mul_f32_e32 v33, 4.0, v31
	v_mul_f32_e32 v35, 4.0, v20
	v_cvt_scalef32_pk_fp4_f32 v1, v29, v32, 1.0 op_sel:[0,0,1,0]
	v_mul_f32_e32 v36, 4.0, v34
	v_mul_f32_e32 v79, 4.0, v21
	v_cvt_scalef32_pk_fp4_f32 v1, v33, v35, 1.0 op_sel:[0,0,0,1]
	v_mul_f32_e32 v38, 4.0, v37
	v_cvt_scalef32_pk_fp4_f32 v1, v36, v79, 1.0 op_sel:[0,0,1,1]
	v_mul_f32_e32 v40, 4.0, v39
	v_cvt_scalef32_pk_f32_fp4 v[2:3], v1, 1.0
	v_fma_f32 v2, v11, 4.0, -v2
	v_cvt_scalef32_pk_f32_fp4 v[4:5], v1, 1.0 op_sel:[1,0,0]
	v_mul_f32_e32 v11, 4.0, v2
	v_fma_f32 v2, v18, 4.0, -v3
	v_mul_f32_e32 v18, 4.0, v2
	v_fma_f32 v2, v26, 4.0, -v4
	v_cvt_scalef32_pk_f32_fp4 v[6:7], v1, 1.0 op_sel:[0,1,0]
	v_mul_f32_e32 v22, 4.0, v2
	v_fma_f32 v2, v19, 4.0, -v5
	v_mul_f32_e32 v19, 4.0, v2
	v_fma_f32 v2, v31, 4.0, -v6
	v_cvt_scalef32_pk_f32_fp4 v[8:9], v1, 1.0 op_sel:[1,1,0]
	v_mul_f32_e32 v26, 4.0, v2
	v_fma_f32 v2, v20, 4.0, -v7
	v_mul_f32_e32 v20, 4.0, v2
	v_fma_f32 v2, v34, 4.0, -v8
	v_mul_f32_e32 v28, 4.0, v2
	v_fma_f32 v2, v21, 4.0, -v9
	v_mul_f32_e32 v21, 4.0, v2
	v_mov_b32_e32 v2, v16
	v_mul_f32_e32 v42, 4.0, v41
	v_mul_f32_e32 v44, 4.0, v43
	v_cvt_scalef32_pk_fp4_f32 v2, v38, v40, 1.0
	v_mul_f32_e32 v46, 4.0, v45
	v_mul_f32_e32 v48, 4.0, v47
	v_cvt_scalef32_pk_fp4_f32 v2, v42, v44, 1.0 op_sel:[0,0,1,0]
	v_mul_f32_e32 v50, 4.0, v49
	v_mul_f32_e32 v52, 4.0, v51
	v_cvt_scalef32_pk_fp4_f32 v2, v46, v48, 1.0 op_sel:[0,0,0,1]
	v_fma_f32 v65, v65, 4.0, -v14
	v_cvt_scalef32_pk_fp4_f32 v2, v50, v52, 1.0 op_sel:[0,0,1,1]
	v_fma_f32 v67, v67, 4.0, -v15
	v_cvt_scalef32_pk_f32_fp4 v[4:5], v2, 1.0
	v_fma_f32 v3, v37, 4.0, -v4
	v_cvt_scalef32_pk_f32_fp4 v[6:7], v2, 1.0 op_sel:[1,0,0]
	v_mul_f32_e32 v29, 4.0, v3
	v_fma_f32 v3, v39, 4.0, -v5
	v_mul_f32_e32 v31, 4.0, v3
	v_fma_f32 v3, v41, 4.0, -v6
	v_cvt_scalef32_pk_f32_fp4 v[8:9], v2, 1.0 op_sel:[0,1,0]
	v_mul_f32_e32 v32, 4.0, v3
	v_fma_f32 v3, v43, 4.0, -v7
	v_mul_f32_e32 v33, 4.0, v3
	v_fma_f32 v3, v45, 4.0, -v8
	v_cvt_scalef32_pk_f32_fp4 v[14:15], v2, 1.0 op_sel:[1,1,0]
	v_mul_f32_e32 v34, 4.0, v3
	v_fma_f32 v3, v47, 4.0, -v9
	v_mul_f32_e32 v35, 4.0, v3
	v_fma_f32 v3, v49, 4.0, -v14
	v_mul_f32_e32 v36, 4.0, v3
	v_fma_f32 v3, v51, 4.0, -v15
	v_mul_f32_e32 v54, 4.0, v53
	v_mul_f32_e32 v56, 4.0, v55
	v_mul_f32_e32 v37, 4.0, v3
	v_mov_b32_e32 v3, v16
	v_mul_f32_e32 v58, 4.0, v57
	v_mul_f32_e32 v60, 4.0, v59
	v_cvt_scalef32_pk_fp4_f32 v3, v54, v56, 1.0
	v_mul_f32_e32 v62, 4.0, v61
	v_mul_f32_e32 v64, 4.0, v63
	v_cvt_scalef32_pk_fp4_f32 v3, v58, v60, 1.0 op_sel:[0,0,1,0]
	v_mul_f32_e32 v66, 4.0, v65
	v_mul_f32_e32 v68, 4.0, v67
	v_cvt_scalef32_pk_fp4_f32 v3, v62, v64, 1.0 op_sel:[0,0,0,1]
	s_nop 0
	v_cvt_scalef32_pk_fp4_f32 v3, v66, v68, 1.0 op_sel:[0,0,1,1]
	ds_write_b128 v10, v[0:3] offset:2048
	v_cvt_scalef32_pk_f32_fp4 v[4:5], v3, 1.0
	v_cvt_scalef32_pk_f32_fp4 v[6:7], v3, 1.0 op_sel:[1,0,0]
	v_fma_f32 v4, v53, 4.0, -v4
	v_fma_f32 v5, v55, 4.0, -v5
	v_cvt_scalef32_pk_f32_fp4 v[8:9], v3, 1.0 op_sel:[0,1,0]
	v_cvt_scalef32_pk_f32_fp4 v[14:15], v3, 1.0 op_sel:[1,1,0]
	v_mul_f32_e32 v4, 4.0, v4
	v_mul_f32_e32 v5, 4.0, v5
	v_fma_f32 v6, v57, 4.0, -v6
	v_fma_f32 v7, v59, 4.0, -v7
	v_mov_b32_e32 v0, v16
	v_mov_b32_e32 v1, v16
	v_mov_b32_e32 v2, v16
	v_mov_b32_e32 v3, v16
	v_mul_f32_e32 v6, 4.0, v6
	v_mul_f32_e32 v7, 4.0, v7
	v_fma_f32 v8, v61, 4.0, -v8
	v_fma_f32 v9, v63, 4.0, -v9
	v_cvt_scalef32_pk_fp4_f32 v0, v69, v13, 1.0
	v_cvt_scalef32_pk_fp4_f32 v1, v11, v18, 1.0
	v_cvt_scalef32_pk_fp4_f32 v2, v29, v31, 1.0
	v_cvt_scalef32_pk_fp4_f32 v3, v4, v5, 1.0
	v_mul_f32_e32 v8, 4.0, v8
	v_mul_f32_e32 v9, 4.0, v9
	v_fma_f32 v14, v65, 4.0, -v14
	v_fma_f32 v15, v67, 4.0, -v15
	v_cvt_scalef32_pk_fp4_f32 v0, v70, v23, 1.0 op_sel:[0,0,1,0]
	v_cvt_scalef32_pk_fp4_f32 v1, v22, v19, 1.0 op_sel:[0,0,1,0]
	v_cvt_scalef32_pk_fp4_f32 v2, v32, v33, 1.0 op_sel:[0,0,1,0]
	v_cvt_scalef32_pk_fp4_f32 v3, v6, v7, 1.0 op_sel:[0,0,1,0]
	v_mul_f32_e32 v14, 4.0, v14
	v_mul_f32_e32 v15, 4.0, v15
	v_cvt_scalef32_pk_fp4_f32 v0, v27, v24, 1.0 op_sel:[0,0,0,1]
	v_cvt_scalef32_pk_fp4_f32 v1, v26, v20, 1.0 op_sel:[0,0,0,1]
	v_cvt_scalef32_pk_fp4_f32 v2, v34, v35, 1.0 op_sel:[0,0,0,1]
	v_cvt_scalef32_pk_fp4_f32 v3, v8, v9, 1.0 op_sel:[0,0,0,1]
	v_cvt_scalef32_pk_fp4_f32 v0, v30, v25, 1.0 op_sel:[0,0,1,1]
	v_cvt_scalef32_pk_fp4_f32 v1, v28, v21, 1.0 op_sel:[0,0,1,1]
	v_cvt_scalef32_pk_fp4_f32 v2, v36, v37, 1.0 op_sel:[0,0,1,1]
	v_cvt_scalef32_pk_fp4_f32 v3, v14, v15, 1.0 op_sel:[0,0,1,1]
	ds_write_b128 v10, v[0:3] offset:3072
	v_lshl_add_u32 v0, v158, 2, v12
	v_add_u32_e32 v13, 0x8000, v0
	ds_read2_b32 v[2:3], v13 offset1:16
	ds_read2_b32 v[6:7], v13 offset0:32 offset1:48
	ds_read2_b32 v[10:11], v13 offset0:64 offset1:80
	s_waitcnt lgkmcnt(2)
	v_ashrrev_i32_e32 v5, 31, v3
	v_mov_b32_e32 v4, v3
	s_waitcnt lgkmcnt(1)
	v_ashrrev_i32_e32 v9, 31, v7
	v_mov_b32_e32 v8, v7
	s_waitcnt lgkmcnt(0)
	v_ashrrev_i32_e32 v15, 31, v11
	v_mov_b32_e32 v14, v11
	v_ashrrev_i32_e32 v1, 31, v2
	v_mov_b32_e32 v0, v2
	v_lshlrev_b64 v[2:3], 10, v[4:5]
	v_ashrrev_i32_e32 v5, 31, v6
	v_mov_b32_e32 v4, v6
	v_lshlrev_b64 v[6:7], 10, v[8:9]
	v_ashrrev_i32_e32 v9, 31, v10
	v_mov_b32_e32 v8, v10
	v_lshlrev_b64 v[10:11], 10, v[14:15]
	ds_read2_b32 v[14:15], v13 offset0:96 offset1:112
	v_lshlrev_b64 v[0:1], 10, v[0:1]
	v_lshl_add_u64 v[0:1], s[12:13], 0, v[0:1]
	v_lshlrev_b64 v[4:5], 10, v[4:5]
	v_lshlrev_b64 v[8:9], 10, v[8:9]
	s_waitcnt lgkmcnt(0)
	v_ashrrev_i32_e32 v19, 31, v14
	v_mov_b32_e32 v18, v14
	v_ashrrev_i32_e32 v21, 31, v15
	v_mov_b32_e32 v20, v15
	v_lshlrev_b64 v[18:19], 10, v[18:19]
	v_lshlrev_b64 v[14:15], 10, v[20:21]
	v_lshl_add_u64 v[0:1], v[0:1], 0, v[152:153]
	v_lshl_add_u64 v[2:3], s[12:13], 0, v[2:3]
	v_lshl_add_u64 v[4:5], s[12:13], 0, v[4:5]
	v_lshl_add_u64 v[6:7], s[12:13], 0, v[6:7]
	v_lshl_add_u64 v[8:9], s[12:13], 0, v[8:9]
	v_lshl_add_u64 v[10:11], s[12:13], 0, v[10:11]
	v_lshl_add_u64 v[18:19], s[12:13], 0, v[18:19]
	v_lshl_add_u64 v[14:15], s[12:13], 0, v[14:15]
	v_lshl_add_u64 v[2:3], v[2:3], 0, v[152:153]
	v_lshl_add_u64 v[4:5], v[4:5], 0, v[152:153]
	v_lshl_add_u64 v[6:7], v[6:7], 0, v[152:153]
	v_lshl_add_u64 v[8:9], v[8:9], 0, v[152:153]
	v_lshl_add_u64 v[10:11], v[10:11], 0, v[152:153]
	v_lshl_add_u64 v[18:19], v[18:19], 0, v[152:153]
	v_lshl_add_u64 v[20:21], v[14:15], 0, v[152:153]
	global_load_dwordx4 v[22:25], v[0:1], off
	global_load_dwordx4 v[26:29], v[0:1], off offset:64
	global_load_dwordx4 v[30:33], v[2:3], off
	global_load_dwordx4 v[34:37], v[2:3], off offset:64
	global_load_dwordx4 v[38:41], v[4:5], off
	global_load_dwordx4 v[42:45], v[4:5], off offset:64
	global_load_dwordx4 v[46:49], v[6:7], off
	global_load_dwordx4 v[56:59], v[6:7], off offset:64
	global_load_dwordx4 v[60:63], v[8:9], off
	global_load_dwordx4 v[64:67], v[8:9], off offset:64
	global_load_dwordx4 v[72:75], v[10:11], off
	global_load_dwordx4 v[76:79], v[10:11], off offset:64
	global_load_dwordx4 v[80:83], v[18:19], off
	global_load_dwordx4 v[84:87], v[18:19], off offset:64
	global_load_dwordx4 v[88:91], v[20:21], off
	global_load_dwordx4 v[92:95], v[20:21], off offset:64
	v_lshlrev_b32_e32 v14, 4, v158
	v_mov_b32_e32 v15, v16
	v_and_b32_e32 v153, 0xffffff80, v224
	v_lshlrev_b32_e32 v13, 10, v154
	v_lshl_add_u64 v[14:15], s[10:11], 0, v[14:15]
	v_add_u32_e32 v225, v12, v153
	v_add3_u32 v70, v216, v13, v152
	v_lshl_add_u64 v[182:183], v[14:15], 0, s[0:1]
	ds_read_b128 v[52:55], v225 offset:32768
	ds_read_b128 v[12:15], v225 offset:32784
	global_load_dwordx4 v[96:99], v[0:1], off offset:128
	global_load_dwordx4 v[100:103], v[0:1], off offset:192
	global_load_dwordx4 v[104:107], v[2:3], off offset:128
	global_load_dwordx4 v[108:111], v[2:3], off offset:192
	global_load_dwordx4 v[112:115], v[4:5], off offset:128
	global_load_dwordx4 v[116:119], v[4:5], off offset:192
	global_load_dwordx4 v[120:123], v[6:7], off offset:128
	global_load_dwordx4 v[124:127], v[6:7], off offset:192
	ds_read_b128 v[128:131], v70 offset:64
	ds_read_b128 v[132:135], v70
	s_waitcnt vmcnt(23) lgkmcnt(0)
	v_mfma_scale_f32_16x16x128_f8f6f4 v[22:25], v[22:25], v[132:135], 0, v187, v187 op_sel_hi:[0,0,0] cbsz:4 blgp:4
	s_waitcnt vmcnt(22)
	v_mfma_scale_f32_16x16x128_f8f6f4 v[22:25], v[26:29], v[128:131], v[22:25], v187, v187 op_sel_hi:[0,0,0] cbsz:4 blgp:4
	s_waitcnt vmcnt(21)
	v_mfma_scale_f32_16x16x128_f8f6f4 v[26:29], v[30:33], v[132:135], 0, v187, v187 op_sel_hi:[0,0,0] cbsz:4 blgp:4
	s_waitcnt vmcnt(20)
	v_mfma_scale_f32_16x16x128_f8f6f4 v[26:29], v[34:37], v[128:131], v[26:29], v187, v187 op_sel_hi:[0,0,0] cbsz:4 blgp:4
	s_waitcnt vmcnt(19)
	v_mfma_scale_f32_16x16x128_f8f6f4 v[30:33], v[38:41], v[132:135], 0, v187, v187 op_sel_hi:[0,0,0] cbsz:4 blgp:4
	s_waitcnt vmcnt(17)
	v_mfma_scale_f32_16x16x128_f8f6f4 v[34:37], v[46:49], v[132:135], 0, v187, v187 op_sel_hi:[0,0,0] cbsz:4 blgp:4
	v_mfma_scale_f32_16x16x128_f8f6f4 v[30:33], v[42:45], v[128:131], v[30:33], v187, v187 op_sel_hi:[0,0,0] cbsz:4 blgp:4
	s_waitcnt vmcnt(16)
	v_mfma_scale_f32_16x16x128_f8f6f4 v[34:37], v[56:59], v[128:131], v[34:37], v187, v187 op_sel_hi:[0,0,0] cbsz:4 blgp:4
	global_load_dwordx4 v[38:41], v[8:9], off offset:128
	global_load_dwordx4 v[42:45], v[8:9], off offset:192
	global_load_dwordx4 v[46:49], v[10:11], off offset:128
	global_load_dwordx4 v[56:59], v[10:11], off offset:192
	global_load_dwordx4 v[136:139], v[18:19], off offset:128
	global_load_dwordx4 v[140:143], v[18:19], off offset:192
	global_load_dwordx4 v[144:147], v[20:21], off offset:128
	global_load_dwordx4 v[160:163], v[20:21], off offset:192
	s_waitcnt vmcnt(23)
	v_mfma_scale_f32_16x16x128_f8f6f4 v[60:63], v[60:63], v[132:135], 0, v187, v187 op_sel_hi:[0,0,0] cbsz:4 blgp:4
	s_waitcnt vmcnt(22)
	v_mfma_scale_f32_16x16x128_f8f6f4 v[60:63], v[64:67], v[128:131], v[60:63], v187, v187 op_sel_hi:[0,0,0] cbsz:4 blgp:4
	s_waitcnt vmcnt(21)
	v_mfma_scale_f32_16x16x128_f8f6f4 v[64:67], v[72:75], v[132:135], 0, v187, v187 op_sel_hi:[0,0,0] cbsz:4 blgp:4
	s_waitcnt vmcnt(20)
	v_mfma_scale_f32_16x16x128_f8f6f4 v[64:67], v[76:79], v[128:131], v[64:67], v187, v187 op_sel_hi:[0,0,0] cbsz:4 blgp:4
	s_waitcnt vmcnt(19)
	v_mfma_scale_f32_16x16x128_f8f6f4 v[72:75], v[80:83], v[132:135], 0, v187, v187 op_sel_hi:[0,0,0] cbsz:4 blgp:4
	s_waitcnt vmcnt(17)
	v_mfma_scale_f32_16x16x128_f8f6f4 v[76:79], v[88:91], v[132:135], 0, v187, v187 op_sel_hi:[0,0,0] cbsz:4 blgp:4
	v_mfma_scale_f32_16x16x128_f8f6f4 v[72:75], v[84:87], v[128:131], v[72:75], v187, v187 op_sel_hi:[0,0,0] cbsz:4 blgp:4
	s_waitcnt vmcnt(16)
	v_mfma_scale_f32_16x16x128_f8f6f4 v[76:79], v[92:95], v[128:131], v[76:79], v187, v187 op_sel_hi:[0,0,0] cbsz:4 blgp:4
	global_load_dwordx4 v[80:83], v[0:1], off offset:256
	global_load_dwordx4 v[84:87], v[0:1], off offset:320
	global_load_dwordx4 v[88:91], v[2:3], off offset:256
	global_load_dwordx4 v[92:95], v[2:3], off offset:320
	global_load_dwordx4 v[128:131], v[4:5], off offset:256
	global_load_dwordx4 v[132:135], v[4:5], off offset:320
	global_load_dwordx4 v[164:167], v[6:7], off offset:256
	global_load_dwordx4 v[168:171], v[6:7], off offset:320
	ds_read_b128 v[172:175], v70 offset:192
	ds_read_b128 v[196:199], v70 offset:128
	s_waitcnt vmcnt(23) lgkmcnt(0)
	v_mfma_scale_f32_16x16x128_f8f6f4 v[22:25], v[96:99], v[196:199], v[22:25], v187, v187 op_sel_hi:[0,0,0] cbsz:4 blgp:4
	s_waitcnt vmcnt(21)
	v_mfma_scale_f32_16x16x128_f8f6f4 v[26:29], v[104:107], v[196:199], v[26:29], v187, v187 op_sel_hi:[0,0,0] cbsz:4 blgp:4
	s_waitcnt vmcnt(19)
	v_mfma_scale_f32_16x16x128_f8f6f4 v[30:33], v[112:115], v[196:199], v[30:33], v187, v187 op_sel_hi:[0,0,0] cbsz:4 blgp:4
	s_waitcnt vmcnt(17)
	v_mfma_scale_f32_16x16x128_f8f6f4 v[34:37], v[120:123], v[196:199], v[34:37], v187, v187 op_sel_hi:[0,0,0] cbsz:4 blgp:4
	v_mfma_scale_f32_16x16x128_f8f6f4 v[22:25], v[100:103], v[172:175], v[22:25], v187, v187 op_sel_hi:[0,0,0] cbsz:4 blgp:4
	v_mfma_scale_f32_16x16x128_f8f6f4 v[26:29], v[108:111], v[172:175], v[26:29], v187, v187 op_sel_hi:[0,0,0] cbsz:4 blgp:4
	v_mfma_scale_f32_16x16x128_f8f6f4 v[30:33], v[116:119], v[172:175], v[30:33], v187, v187 op_sel_hi:[0,0,0] cbsz:4 blgp:4
	s_waitcnt vmcnt(16)
	v_mfma_scale_f32_16x16x128_f8f6f4 v[34:37], v[124:127], v[172:175], v[34:37], v187, v187 op_sel_hi:[0,0,0] cbsz:4 blgp:4
	global_load_dwordx4 v[96:99], v[8:9], off offset:256
	global_load_dwordx4 v[100:103], v[8:9], off offset:320
	global_load_dwordx4 v[104:107], v[10:11], off offset:256
	global_load_dwordx4 v[108:111], v[10:11], off offset:320
	global_load_dwordx4 v[112:115], v[18:19], off offset:256
	global_load_dwordx4 v[116:119], v[18:19], off offset:320
	global_load_dwordx4 v[120:123], v[20:21], off offset:256
	global_load_dwordx4 v[124:127], v[20:21], off offset:320
	s_waitcnt vmcnt(23)
	v_mfma_scale_f32_16x16x128_f8f6f4 v[38:41], v[38:41], v[196:199], v[60:63], v187, v187 op_sel_hi:[0,0,0] cbsz:4 blgp:4
	s_waitcnt vmcnt(22)
	v_mfma_scale_f32_16x16x128_f8f6f4 v[38:41], v[42:45], v[172:175], v[38:41], v187, v187 op_sel_hi:[0,0,0] cbsz:4 blgp:4
	s_waitcnt vmcnt(21)
	v_mfma_scale_f32_16x16x128_f8f6f4 v[42:45], v[46:49], v[196:199], v[64:67], v187, v187 op_sel_hi:[0,0,0] cbsz:4 blgp:4
	s_waitcnt vmcnt(20)
	v_mfma_scale_f32_16x16x128_f8f6f4 v[42:45], v[56:59], v[172:175], v[42:45], v187, v187 op_sel_hi:[0,0,0] cbsz:4 blgp:4
	s_waitcnt vmcnt(19)
	v_mfma_scale_f32_16x16x128_f8f6f4 v[46:49], v[136:139], v[196:199], v[72:75], v187, v187 op_sel_hi:[0,0,0] cbsz:4 blgp:4
	s_waitcnt vmcnt(17)
	v_mfma_scale_f32_16x16x128_f8f6f4 v[56:59], v[144:147], v[196:199], v[76:79], v187, v187 op_sel_hi:[0,0,0] cbsz:4 blgp:4
	v_mfma_scale_f32_16x16x128_f8f6f4 v[46:49], v[140:143], v[172:175], v[46:49], v187, v187 op_sel_hi:[0,0,0] cbsz:4 blgp:4
	s_waitcnt vmcnt(16)
	v_mfma_scale_f32_16x16x128_f8f6f4 v[56:59], v[160:163], v[172:175], v[56:59], v187, v187 op_sel_hi:[0,0,0] cbsz:4 blgp:4
	global_load_dwordx4 v[60:63], v[0:1], off offset:384
	global_load_dwordx4 v[64:67], v[0:1], off offset:448
	global_load_dwordx4 v[72:75], v[2:3], off offset:384
	global_load_dwordx4 v[76:79], v[2:3], off offset:448
	global_load_dwordx4 v[136:139], v[4:5], off offset:384
	global_load_dwordx4 v[140:143], v[4:5], off offset:448
	global_load_dwordx4 v[144:147], v[6:7], off offset:384
	global_load_dwordx4 v[160:163], v[6:7], off offset:448
	ds_read_b128 v[172:175], v70 offset:320
	ds_read_b128 v[196:199], v70 offset:256
	s_waitcnt vmcnt(23) lgkmcnt(0)
	v_mfma_scale_f32_16x16x128_f8f6f4 v[22:25], v[80:83], v[196:199], v[22:25], v187, v187 op_sel_hi:[0,0,0] cbsz:4 blgp:4
	s_waitcnt vmcnt(21)
	v_mfma_scale_f32_16x16x128_f8f6f4 v[26:29], v[88:91], v[196:199], v[26:29], v187, v187 op_sel_hi:[0,0,0] cbsz:4 blgp:4
	s_waitcnt vmcnt(19)
	v_mfma_scale_f32_16x16x128_f8f6f4 v[30:33], v[128:131], v[196:199], v[30:33], v187, v187 op_sel_hi:[0,0,0] cbsz:4 blgp:4
	s_waitcnt vmcnt(17)
	v_mfma_scale_f32_16x16x128_f8f6f4 v[34:37], v[164:167], v[196:199], v[34:37], v187, v187 op_sel_hi:[0,0,0] cbsz:4 blgp:4
	v_mfma_scale_f32_16x16x128_f8f6f4 v[22:25], v[84:87], v[172:175], v[22:25], v187, v187 op_sel_hi:[0,0,0] cbsz:4 blgp:4
	v_mfma_scale_f32_16x16x128_f8f6f4 v[26:29], v[92:95], v[172:175], v[26:29], v187, v187 op_sel_hi:[0,0,0] cbsz:4 blgp:4
	v_mfma_scale_f32_16x16x128_f8f6f4 v[30:33], v[132:135], v[172:175], v[30:33], v187, v187 op_sel_hi:[0,0,0] cbsz:4 blgp:4
	s_waitcnt vmcnt(16)
	v_mfma_scale_f32_16x16x128_f8f6f4 v[34:37], v[168:171], v[172:175], v[34:37], v187, v187 op_sel_hi:[0,0,0] cbsz:4 blgp:4
	global_load_dwordx4 v[80:83], v[8:9], off offset:384
	global_load_dwordx4 v[84:87], v[8:9], off offset:448
	global_load_dwordx4 v[88:91], v[10:11], off offset:384
	global_load_dwordx4 v[92:95], v[10:11], off offset:448
	global_load_dwordx4 v[128:131], v[18:19], off offset:384
	global_load_dwordx4 v[132:135], v[18:19], off offset:448
	global_load_dwordx4 v[164:167], v[20:21], off offset:384
	global_load_dwordx4 v[168:171], v[20:21], off offset:448
	s_waitcnt vmcnt(23)
	v_mfma_scale_f32_16x16x128_f8f6f4 v[38:41], v[96:99], v[196:199], v[38:41], v187, v187 op_sel_hi:[0,0,0] cbsz:4 blgp:4
	s_waitcnt vmcnt(21)
	v_mfma_scale_f32_16x16x128_f8f6f4 v[42:45], v[104:107], v[196:199], v[42:45], v187, v187 op_sel_hi:[0,0,0] cbsz:4 blgp:4
	s_waitcnt vmcnt(19)
	v_mfma_scale_f32_16x16x128_f8f6f4 v[46:49], v[112:115], v[196:199], v[46:49], v187, v187 op_sel_hi:[0,0,0] cbsz:4 blgp:4
	s_waitcnt vmcnt(17)
	v_mfma_scale_f32_16x16x128_f8f6f4 v[56:59], v[120:123], v[196:199], v[56:59], v187, v187 op_sel_hi:[0,0,0] cbsz:4 blgp:4
	v_mfma_scale_f32_16x16x128_f8f6f4 v[38:41], v[100:103], v[172:175], v[38:41], v187, v187 op_sel_hi:[0,0,0] cbsz:4 blgp:4
	v_mfma_scale_f32_16x16x128_f8f6f4 v[42:45], v[108:111], v[172:175], v[42:45], v187, v187 op_sel_hi:[0,0,0] cbsz:4 blgp:4
	v_mfma_scale_f32_16x16x128_f8f6f4 v[46:49], v[116:119], v[172:175], v[46:49], v187, v187 op_sel_hi:[0,0,0] cbsz:4 blgp:4
	s_waitcnt vmcnt(16)
	v_mfma_scale_f32_16x16x128_f8f6f4 v[56:59], v[124:127], v[172:175], v[56:59], v187, v187 op_sel_hi:[0,0,0] cbsz:4 blgp:4
	global_load_dwordx4 v[96:99], v[0:1], off offset:512
	global_load_dwordx4 v[100:103], v[0:1], off offset:576
	global_load_dwordx4 v[104:107], v[2:3], off offset:512
	global_load_dwordx4 v[108:111], v[2:3], off offset:576
	global_load_dwordx4 v[112:115], v[4:5], off offset:512
	global_load_dwordx4 v[116:119], v[4:5], off offset:576
	global_load_dwordx4 v[120:123], v[6:7], off offset:512
	global_load_dwordx4 v[124:127], v[6:7], off offset:576
	ds_read_b128 v[172:175], v70 offset:448
	ds_read_b128 v[196:199], v70 offset:384
	s_waitcnt vmcnt(23) lgkmcnt(0)
	v_mfma_scale_f32_16x16x128_f8f6f4 v[22:25], v[60:63], v[196:199], v[22:25], v187, v187 op_sel_hi:[0,0,0] cbsz:4 blgp:4
	s_waitcnt vmcnt(21)
	v_mfma_scale_f32_16x16x128_f8f6f4 v[26:29], v[72:75], v[196:199], v[26:29], v187, v187 op_sel_hi:[0,0,0] cbsz:4 blgp:4
	s_waitcnt vmcnt(19)
	v_mfma_scale_f32_16x16x128_f8f6f4 v[30:33], v[136:139], v[196:199], v[30:33], v187, v187 op_sel_hi:[0,0,0] cbsz:4 blgp:4
	s_waitcnt vmcnt(17)
	v_mfma_scale_f32_16x16x128_f8f6f4 v[34:37], v[144:147], v[196:199], v[34:37], v187, v187 op_sel_hi:[0,0,0] cbsz:4 blgp:4
	v_mfma_scale_f32_16x16x128_f8f6f4 v[22:25], v[64:67], v[172:175], v[22:25], v187, v187 op_sel_hi:[0,0,0] cbsz:4 blgp:4
	v_mfma_scale_f32_16x16x128_f8f6f4 v[26:29], v[76:79], v[172:175], v[26:29], v187, v187 op_sel_hi:[0,0,0] cbsz:4 blgp:4
	v_mfma_scale_f32_16x16x128_f8f6f4 v[30:33], v[140:143], v[172:175], v[30:33], v187, v187 op_sel_hi:[0,0,0] cbsz:4 blgp:4
	s_waitcnt vmcnt(16)
	v_mfma_scale_f32_16x16x128_f8f6f4 v[34:37], v[160:163], v[172:175], v[34:37], v187, v187 op_sel_hi:[0,0,0] cbsz:4 blgp:4
	global_load_dwordx4 v[60:63], v[8:9], off offset:512
	global_load_dwordx4 v[64:67], v[8:9], off offset:576
	global_load_dwordx4 v[72:75], v[10:11], off offset:512
	global_load_dwordx4 v[76:79], v[10:11], off offset:576
	global_load_dwordx4 v[136:139], v[18:19], off offset:512
	global_load_dwordx4 v[140:143], v[18:19], off offset:576
	global_load_dwordx4 v[144:147], v[20:21], off offset:512
	global_load_dwordx4 v[160:163], v[20:21], off offset:576
	s_waitcnt vmcnt(23)
	v_mfma_scale_f32_16x16x128_f8f6f4 v[38:41], v[80:83], v[196:199], v[38:41], v187, v187 op_sel_hi:[0,0,0] cbsz:4 blgp:4
	s_waitcnt vmcnt(21)
	v_mfma_scale_f32_16x16x128_f8f6f4 v[42:45], v[88:91], v[196:199], v[42:45], v187, v187 op_sel_hi:[0,0,0] cbsz:4 blgp:4
	s_waitcnt vmcnt(19)
	v_mfma_scale_f32_16x16x128_f8f6f4 v[46:49], v[128:131], v[196:199], v[46:49], v187, v187 op_sel_hi:[0,0,0] cbsz:4 blgp:4
	s_waitcnt vmcnt(17)
	v_mfma_scale_f32_16x16x128_f8f6f4 v[56:59], v[164:167], v[196:199], v[56:59], v187, v187 op_sel_hi:[0,0,0] cbsz:4 blgp:4
	v_mfma_scale_f32_16x16x128_f8f6f4 v[38:41], v[84:87], v[172:175], v[38:41], v187, v187 op_sel_hi:[0,0,0] cbsz:4 blgp:4
	v_mfma_scale_f32_16x16x128_f8f6f4 v[42:45], v[92:95], v[172:175], v[42:45], v187, v187 op_sel_hi:[0,0,0] cbsz:4 blgp:4
	v_mfma_scale_f32_16x16x128_f8f6f4 v[46:49], v[132:135], v[172:175], v[46:49], v187, v187 op_sel_hi:[0,0,0] cbsz:4 blgp:4
	s_waitcnt vmcnt(16)
	v_mfma_scale_f32_16x16x128_f8f6f4 v[56:59], v[168:171], v[172:175], v[56:59], v187, v187 op_sel_hi:[0,0,0] cbsz:4 blgp:4
	global_load_dwordx4 v[80:83], v[0:1], off offset:640
	global_load_dwordx4 v[84:87], v[0:1], off offset:704
	global_load_dwordx4 v[88:91], v[2:3], off offset:640
	global_load_dwordx4 v[92:95], v[2:3], off offset:704
	global_load_dwordx4 v[128:131], v[4:5], off offset:640
	global_load_dwordx4 v[132:135], v[4:5], off offset:704
	global_load_dwordx4 v[164:167], v[6:7], off offset:640
	global_load_dwordx4 v[168:171], v[6:7], off offset:704
	ds_read_b128 v[172:175], v70 offset:576
	ds_read_b128 v[196:199], v70 offset:512
	s_waitcnt vmcnt(23) lgkmcnt(0)
	v_mfma_scale_f32_16x16x128_f8f6f4 v[22:25], v[96:99], v[196:199], v[22:25], v187, v187 op_sel_hi:[0,0,0] cbsz:4 blgp:4
	s_waitcnt vmcnt(21)
	v_mfma_scale_f32_16x16x128_f8f6f4 v[26:29], v[104:107], v[196:199], v[26:29], v187, v187 op_sel_hi:[0,0,0] cbsz:4 blgp:4
	s_waitcnt vmcnt(19)
	v_mfma_scale_f32_16x16x128_f8f6f4 v[30:33], v[112:115], v[196:199], v[30:33], v187, v187 op_sel_hi:[0,0,0] cbsz:4 blgp:4
	s_waitcnt vmcnt(17)
	v_mfma_scale_f32_16x16x128_f8f6f4 v[34:37], v[120:123], v[196:199], v[34:37], v187, v187 op_sel_hi:[0,0,0] cbsz:4 blgp:4
	v_mfma_scale_f32_16x16x128_f8f6f4 v[22:25], v[100:103], v[172:175], v[22:25], v187, v187 op_sel_hi:[0,0,0] cbsz:4 blgp:4
	v_mfma_scale_f32_16x16x128_f8f6f4 v[26:29], v[108:111], v[172:175], v[26:29], v187, v187 op_sel_hi:[0,0,0] cbsz:4 blgp:4
	v_mfma_scale_f32_16x16x128_f8f6f4 v[30:33], v[116:119], v[172:175], v[30:33], v187, v187 op_sel_hi:[0,0,0] cbsz:4 blgp:4
	s_waitcnt vmcnt(16)
	v_mfma_scale_f32_16x16x128_f8f6f4 v[34:37], v[124:127], v[172:175], v[34:37], v187, v187 op_sel_hi:[0,0,0] cbsz:4 blgp:4
	global_load_dwordx4 v[96:99], v[8:9], off offset:640
	global_load_dwordx4 v[100:103], v[8:9], off offset:704
	global_load_dwordx4 v[104:107], v[10:11], off offset:640
	global_load_dwordx4 v[108:111], v[10:11], off offset:704
	global_load_dwordx4 v[112:115], v[18:19], off offset:640
	global_load_dwordx4 v[116:119], v[18:19], off offset:704
	global_load_dwordx4 v[120:123], v[20:21], off offset:640
	global_load_dwordx4 v[124:127], v[20:21], off offset:704
	s_waitcnt vmcnt(23)
	v_mfma_scale_f32_16x16x128_f8f6f4 v[38:41], v[60:63], v[196:199], v[38:41], v187, v187 op_sel_hi:[0,0,0] cbsz:4 blgp:4
	s_waitcnt vmcnt(21)
	v_mfma_scale_f32_16x16x128_f8f6f4 v[42:45], v[72:75], v[196:199], v[42:45], v187, v187 op_sel_hi:[0,0,0] cbsz:4 blgp:4
	s_waitcnt vmcnt(19)
	v_mfma_scale_f32_16x16x128_f8f6f4 v[46:49], v[136:139], v[196:199], v[46:49], v187, v187 op_sel_hi:[0,0,0] cbsz:4 blgp:4
	s_waitcnt vmcnt(17)
	v_mfma_scale_f32_16x16x128_f8f6f4 v[56:59], v[144:147], v[196:199], v[56:59], v187, v187 op_sel_hi:[0,0,0] cbsz:4 blgp:4
	v_mfma_scale_f32_16x16x128_f8f6f4 v[38:41], v[64:67], v[172:175], v[38:41], v187, v187 op_sel_hi:[0,0,0] cbsz:4 blgp:4
	v_mfma_scale_f32_16x16x128_f8f6f4 v[42:45], v[76:79], v[172:175], v[42:45], v187, v187 op_sel_hi:[0,0,0] cbsz:4 blgp:4
	v_mfma_scale_f32_16x16x128_f8f6f4 v[46:49], v[140:143], v[172:175], v[46:49], v187, v187 op_sel_hi:[0,0,0] cbsz:4 blgp:4
	s_waitcnt vmcnt(16)
	v_mfma_scale_f32_16x16x128_f8f6f4 v[56:59], v[160:163], v[172:175], v[56:59], v187, v187 op_sel_hi:[0,0,0] cbsz:4 blgp:4
	global_load_dwordx4 v[60:63], v[0:1], off offset:768
	global_load_dwordx4 v[64:67], v[0:1], off offset:832
	global_load_dwordx4 v[72:75], v[2:3], off offset:768
	global_load_dwordx4 v[76:79], v[2:3], off offset:832
	global_load_dwordx4 v[136:139], v[4:5], off offset:768
	global_load_dwordx4 v[140:143], v[4:5], off offset:832
	global_load_dwordx4 v[144:147], v[6:7], off offset:768
	global_load_dwordx4 v[160:163], v[6:7], off offset:832
	ds_read_b128 v[172:175], v70 offset:704
	ds_read_b128 v[196:199], v70 offset:640
	s_waitcnt vmcnt(23) lgkmcnt(0)
	v_mfma_scale_f32_16x16x128_f8f6f4 v[22:25], v[80:83], v[196:199], v[22:25], v187, v187 op_sel_hi:[0,0,0] cbsz:4 blgp:4
	s_waitcnt vmcnt(21)
	v_mfma_scale_f32_16x16x128_f8f6f4 v[26:29], v[88:91], v[196:199], v[26:29], v187, v187 op_sel_hi:[0,0,0] cbsz:4 blgp:4
	s_waitcnt vmcnt(19)
	v_mfma_scale_f32_16x16x128_f8f6f4 v[30:33], v[128:131], v[196:199], v[30:33], v187, v187 op_sel_hi:[0,0,0] cbsz:4 blgp:4
	s_waitcnt vmcnt(17)
	v_mfma_scale_f32_16x16x128_f8f6f4 v[34:37], v[164:167], v[196:199], v[34:37], v187, v187 op_sel_hi:[0,0,0] cbsz:4 blgp:4
	v_mfma_scale_f32_16x16x128_f8f6f4 v[22:25], v[84:87], v[172:175], v[22:25], v187, v187 op_sel_hi:[0,0,0] cbsz:4 blgp:4
	v_mfma_scale_f32_16x16x128_f8f6f4 v[26:29], v[92:95], v[172:175], v[26:29], v187, v187 op_sel_hi:[0,0,0] cbsz:4 blgp:4
	v_mfma_scale_f32_16x16x128_f8f6f4 v[30:33], v[132:135], v[172:175], v[30:33], v187, v187 op_sel_hi:[0,0,0] cbsz:4 blgp:4
	s_waitcnt vmcnt(16)
	v_mfma_scale_f32_16x16x128_f8f6f4 v[34:37], v[168:171], v[172:175], v[34:37], v187, v187 op_sel_hi:[0,0,0] cbsz:4 blgp:4
	global_load_dwordx4 v[80:83], v[8:9], off offset:768
	global_load_dwordx4 v[84:87], v[8:9], off offset:832
	global_load_dwordx4 v[88:91], v[10:11], off offset:768
	global_load_dwordx4 v[92:95], v[10:11], off offset:832
	global_load_dwordx4 v[128:131], v[18:19], off offset:768
	global_load_dwordx4 v[132:135], v[18:19], off offset:832
	global_load_dwordx4 v[164:167], v[20:21], off offset:768
	global_load_dwordx4 v[168:171], v[20:21], off offset:832
	s_waitcnt vmcnt(23)
	v_mfma_scale_f32_16x16x128_f8f6f4 v[38:41], v[96:99], v[196:199], v[38:41], v187, v187 op_sel_hi:[0,0,0] cbsz:4 blgp:4
	s_waitcnt vmcnt(21)
	v_mfma_scale_f32_16x16x128_f8f6f4 v[42:45], v[104:107], v[196:199], v[42:45], v187, v187 op_sel_hi:[0,0,0] cbsz:4 blgp:4
	s_waitcnt vmcnt(19)
	v_mfma_scale_f32_16x16x128_f8f6f4 v[46:49], v[112:115], v[196:199], v[46:49], v187, v187 op_sel_hi:[0,0,0] cbsz:4 blgp:4
	s_waitcnt vmcnt(17)
	v_mfma_scale_f32_16x16x128_f8f6f4 v[56:59], v[120:123], v[196:199], v[56:59], v187, v187 op_sel_hi:[0,0,0] cbsz:4 blgp:4
	v_mfma_scale_f32_16x16x128_f8f6f4 v[38:41], v[100:103], v[172:175], v[38:41], v187, v187 op_sel_hi:[0,0,0] cbsz:4 blgp:4
	v_mfma_scale_f32_16x16x128_f8f6f4 v[42:45], v[108:111], v[172:175], v[42:45], v187, v187 op_sel_hi:[0,0,0] cbsz:4 blgp:4
	v_mfma_scale_f32_16x16x128_f8f6f4 v[46:49], v[116:119], v[172:175], v[46:49], v187, v187 op_sel_hi:[0,0,0] cbsz:4 blgp:4
	s_waitcnt vmcnt(16)
	v_mfma_scale_f32_16x16x128_f8f6f4 v[56:59], v[124:127], v[172:175], v[56:59], v187, v187 op_sel_hi:[0,0,0] cbsz:4 blgp:4
	global_load_dwordx4 v[96:99], v[0:1], off offset:896
	global_load_dwordx4 v[100:103], v[0:1], off offset:960
	global_load_dwordx4 v[104:107], v[2:3], off offset:896
	global_load_dwordx4 v[108:111], v[2:3], off offset:960
	global_load_dwordx4 v[112:115], v[4:5], off offset:896
	global_load_dwordx4 v[116:119], v[4:5], off offset:960
	global_load_dwordx4 v[120:123], v[6:7], off offset:896
	global_load_dwordx4 v[124:127], v[6:7], off offset:960
	ds_read_b128 v[0:3], v70 offset:832
	ds_read_b128 v[4:7], v70 offset:768
	s_waitcnt vmcnt(23) lgkmcnt(0)
	v_mfma_scale_f32_16x16x128_f8f6f4 v[22:25], v[60:63], v[4:7], v[22:25], v187, v187 op_sel_hi:[0,0,0] cbsz:4 blgp:4
	s_waitcnt vmcnt(22)
	v_mfma_scale_f32_16x16x128_f8f6f4 v[172:175], v[64:67], v[0:3], v[22:25], v187, v187 op_sel_hi:[0,0,0] cbsz:4 blgp:4
	s_waitcnt vmcnt(21)
	v_mfma_scale_f32_16x16x128_f8f6f4 v[22:25], v[72:75], v[4:7], v[26:29], v187, v187 op_sel_hi:[0,0,0] cbsz:4 blgp:4
	s_waitcnt vmcnt(20)
	v_mfma_scale_f32_16x16x128_f8f6f4 v[72:75], v[76:79], v[0:3], v[22:25], v187, v187 op_sel_hi:[0,0,0] cbsz:4 blgp:4
	s_waitcnt vmcnt(19)
	v_mfma_scale_f32_16x16x128_f8f6f4 v[22:25], v[136:139], v[4:7], v[30:33], v187, v187 op_sel_hi:[0,0,0] cbsz:4 blgp:4
	s_waitcnt vmcnt(18)
	v_mfma_scale_f32_16x16x128_f8f6f4 v[76:79], v[140:143], v[0:3], v[22:25], v187, v187 op_sel_hi:[0,0,0] cbsz:4 blgp:4
	s_waitcnt vmcnt(17)
	v_mfma_scale_f32_16x16x128_f8f6f4 v[22:25], v[144:147], v[4:7], v[34:37], v187, v187 op_sel_hi:[0,0,0] cbsz:4 blgp:4
	s_waitcnt vmcnt(16)
	v_mfma_scale_f32_16x16x128_f8f6f4 v[160:163], v[160:163], v[0:3], v[22:25], v187, v187 op_sel_hi:[0,0,0] cbsz:4 blgp:4
	global_load_dwordx4 v[196:199], v[8:9], off offset:896
	global_load_dwordx4 v[200:203], v[8:9], off offset:960
	global_load_dwordx4 v[204:207], v[10:11], off offset:896
	global_load_dwordx4 v[208:211], v[10:11], off offset:960
	global_load_dwordx4 v[226:229], v[18:19], off offset:896
	global_load_dwordx4 v[230:233], v[18:19], off offset:960
	global_load_dwordx4 v[234:237], v[20:21], off offset:896
	global_load_dwordx4 v[238:241], v[20:21], off offset:960
	s_waitcnt vmcnt(23)
	v_mfma_scale_f32_16x16x128_f8f6f4 v[8:11], v[80:83], v[4:7], v[38:41], v187, v187 op_sel_hi:[0,0,0] cbsz:4 blgp:4
	s_waitcnt vmcnt(22)
	v_mfma_scale_f32_16x16x128_f8f6f4 v[80:83], v[84:87], v[0:3], v[8:11], v187, v187 op_sel_hi:[0,0,0] cbsz:4 blgp:4
	s_waitcnt vmcnt(21)
	v_mfma_scale_f32_16x16x128_f8f6f4 v[8:11], v[88:91], v[4:7], v[42:45], v187, v187 op_sel_hi:[0,0,0] cbsz:4 blgp:4
	s_waitcnt vmcnt(20)
	v_mfma_scale_f32_16x16x128_f8f6f4 v[84:87], v[92:95], v[0:3], v[8:11], v187, v187 op_sel_hi:[0,0,0] cbsz:4 blgp:4
	s_waitcnt vmcnt(19)
	v_mfma_scale_f32_16x16x128_f8f6f4 v[8:11], v[128:131], v[4:7], v[46:49], v187, v187 op_sel_hi:[0,0,0] cbsz:4 blgp:4
	s_waitcnt vmcnt(17)
	v_mfma_scale_f32_16x16x128_f8f6f4 v[4:7], v[164:167], v[4:7], v[56:59], v187, v187 op_sel_hi:[0,0,0] cbsz:4 blgp:4
	v_mfma_scale_f32_16x16x128_f8f6f4 v[88:91], v[132:135], v[0:3], v[8:11], v187, v187 op_sel_hi:[0,0,0] cbsz:4 blgp:4
	s_waitcnt vmcnt(16)
	v_mfma_scale_f32_16x16x128_f8f6f4 v[92:95], v[168:171], v[0:3], v[4:7], v187, v187 op_sel_hi:[0,0,0] cbsz:4 blgp:4
	v_mov_b32_e32 v0, v52
	v_mov_b32_e32 v1, v16
	v_mov_b32_e32 v22, v53
	v_mov_b32_e32 v23, v16
	v_mov_b32_e32 v38, v54
	v_mov_b32_e32 v39, v16
	v_mov_b32_e32 v54, v55
	v_mov_b32_e32 v55, v16
	v_lshlrev_b64 v[0:1], 10, v[0:1]
	v_lshlrev_b64 v[22:23], 10, v[22:23]
	v_lshlrev_b64 v[38:39], 10, v[38:39]
	v_lshlrev_b64 v[54:55], 10, v[54:55]
	v_lshl_add_u64 v[18:19], v[182:183], 0, v[0:1]
	v_lshl_add_u64 v[34:35], v[182:183], 0, v[22:23]
	v_lshl_add_u64 v[50:51], v[182:183], 0, v[38:39]
	v_lshl_add_u64 v[66:67], v[182:183], 0, v[54:55]
	global_load_dwordx4 v[0:3], v[18:19], off
	global_load_dwordx4 v[4:7], v[18:19], off offset:256
	global_load_dwordx4 v[8:11], v[18:19], off offset:512
	s_nop 0
	global_load_dwordx4 v[18:21], v[18:19], off offset:768
	s_nop 0
	global_load_dwordx4 v[22:25], v[34:35], off
	global_load_dwordx4 v[26:29], v[34:35], off offset:256
	global_load_dwordx4 v[30:33], v[34:35], off offset:512
	s_nop 0
	global_load_dwordx4 v[34:37], v[34:35], off offset:768
	s_nop 0
	global_load_dwordx4 v[38:41], v[50:51], off
	global_load_dwordx4 v[42:45], v[50:51], off offset:256
	global_load_dwordx4 v[46:49], v[50:51], off offset:512
	s_nop 0
	global_load_dwordx4 v[50:53], v[50:51], off offset:768
	s_nop 0
	global_load_dwordx4 v[54:57], v[66:67], off
	global_load_dwordx4 v[58:61], v[66:67], off offset:256
	global_load_dwordx4 v[62:65], v[66:67], off offset:512
	s_nop 0
	global_load_dwordx4 v[66:69], v[66:67], off offset:768
	ds_read_b128 v[164:167], v70 offset:960
	ds_read_b128 v[168:171], v70 offset:896
	s_waitcnt vmcnt(29) lgkmcnt(0)
	v_mfma_scale_f32_16x16x128_f8f6f4 v[70:73], v[104:107], v[168:171], v[72:75], v187, v187 op_sel_hi:[0,0,0] cbsz:4 blgp:4
	s_waitcnt vmcnt(28)
	v_mfma_scale_f32_16x16x128_f8f6f4 v[142:145], v[108:111], v[164:167], v[70:73], v187, v187 op_sel_hi:[0,0,0] cbsz:4 blgp:4
	s_waitcnt vmcnt(27)
	v_mfma_scale_f32_16x16x128_f8f6f4 v[70:73], v[112:115], v[168:171], v[76:79], v187, v187 op_sel_hi:[0,0,0] cbsz:4 blgp:4
	v_mfma_scale_f32_16x16x128_f8f6f4 v[96:99], v[96:99], v[168:171], v[172:175], v187, v187 op_sel_hi:[0,0,0] cbsz:4 blgp:4
	s_waitcnt vmcnt(26)
	v_mfma_scale_f32_16x16x128_f8f6f4 v[138:141], v[116:119], v[164:167], v[70:73], v187, v187 op_sel_hi:[0,0,0] cbsz:4 blgp:4
	s_waitcnt vmcnt(25)
	v_mfma_scale_f32_16x16x128_f8f6f4 v[70:73], v[120:123], v[168:171], v[160:163], v187, v187 op_sel_hi:[0,0,0] cbsz:4 blgp:4
	v_mfma_scale_f32_16x16x128_f8f6f4 v[146:149], v[100:103], v[164:167], v[96:99], v187, v187 op_sel_hi:[0,0,0] cbsz:4 blgp:4
	s_waitcnt vmcnt(24)
	v_mfma_scale_f32_16x16x128_f8f6f4 v[134:137], v[124:127], v[164:167], v[70:73], v187, v187 op_sel_hi:[0,0,0] cbsz:4 blgp:4
	s_waitcnt vmcnt(23)
	v_mfma_scale_f32_16x16x128_f8f6f4 v[70:73], v[196:199], v[168:171], v[80:83], v187, v187 op_sel_hi:[0,0,0] cbsz:4 blgp:4
	s_waitcnt vmcnt(22)
	v_mfma_scale_f32_16x16x128_f8f6f4 v[130:133], v[200:203], v[164:167], v[70:73], v187, v187 op_sel_hi:[0,0,0] cbsz:4 blgp:4
	s_waitcnt vmcnt(21)
	v_mfma_scale_f32_16x16x128_f8f6f4 v[70:73], v[204:207], v[168:171], v[84:87], v187, v187 op_sel_hi:[0,0,0] cbsz:4 blgp:4
	s_waitcnt vmcnt(20)
	v_mfma_scale_f32_16x16x128_f8f6f4 v[126:129], v[208:211], v[164:167], v[70:73], v187, v187 op_sel_hi:[0,0,0] cbsz:4 blgp:4
	s_waitcnt vmcnt(19)
	v_mfma_scale_f32_16x16x128_f8f6f4 v[70:73], v[226:229], v[168:171], v[88:91], v187, v187 op_sel_hi:[0,0,0] cbsz:4 blgp:4
	s_waitcnt vmcnt(18)
	v_mfma_scale_f32_16x16x128_f8f6f4 v[122:125], v[230:233], v[164:167], v[70:73], v187, v187 op_sel_hi:[0,0,0] cbsz:4 blgp:4
	s_waitcnt vmcnt(17)
	v_mfma_scale_f32_16x16x128_f8f6f4 v[70:73], v[234:237], v[168:171], v[92:95], v187, v187 op_sel_hi:[0,0,0] cbsz:4 blgp:4
	s_waitcnt vmcnt(16)
	v_mfma_scale_f32_16x16x128_f8f6f4 v[118:121], v[238:241], v[164:167], v[70:73], v187, v187 op_sel_hi:[0,0,0] cbsz:4 blgp:4
	s_nop 5
	v_mov_b32_e32 v70, v12
	v_mov_b32_e32 v71, v16
	v_mov_b32_e32 v12, v13
	v_mov_b32_e32 v13, v16
	v_lshlrev_b64 v[70:71], 10, v[70:71]
	v_lshlrev_b64 v[12:13], 10, v[12:13]
	v_lshl_add_u64 v[82:83], v[182:183], 0, v[70:71]
	v_lshl_add_u64 v[12:13], v[182:183], 0, v[12:13]
	global_load_dwordx4 v[70:73], v[82:83], off
	global_load_dwordx4 v[74:77], v[82:83], off offset:256
	global_load_dwordx4 v[78:81], v[82:83], off offset:512
	s_nop 0
	global_load_dwordx4 v[82:85], v[82:83], off offset:768
	s_nop 0
	global_load_dwordx4 v[86:89], v[12:13], off
	global_load_dwordx4 v[90:93], v[12:13], off offset:256
	global_load_dwordx4 v[94:97], v[12:13], off offset:512
	global_load_dwordx4 v[98:101], v[12:13], off offset:768
	v_mov_b32_e32 v12, v14
	v_mov_b32_e32 v13, v16
	v_lshlrev_b64 v[12:13], 10, v[12:13]
	v_lshl_add_u64 v[12:13], v[182:183], 0, v[12:13]
	global_load_dwordx4 v[102:105], v[12:13], off
	global_load_dwordx4 v[106:109], v[12:13], off offset:256
	global_load_dwordx4 v[110:113], v[12:13], off offset:512
	global_load_dwordx4 v[114:117], v[12:13], off offset:768
	v_cmp_lt_i32_e32 vcc, 0, v154
	v_mov_b32_e32 v12, 0x3d321643
	s_and_saveexec_b64 s[10:11], vcc
	s_cbranch_execz .LBB0_738
	v_cmp_ne_u32_e32 vcc, 1, v154
	s_and_saveexec_b64 s[12:13], vcc
	s_xor_b64 s[12:13], exec, s[12:13]
	v_cmp_eq_u32_e32 vcc, 2, v154
	v_mov_b32_e32 v12, 0x3a321643
	v_mov_b32_e32 v13, 0x3b321643
	v_cndmask_b32_e32 v12, v12, v13, vcc
	s_andn2_saveexec_b64 s[12:13], s[12:13]
	v_mov_b32_e32 v12, 0x3c321643
	s_or_b64 exec, exec, s[12:13]
	s_nop 0
